# attention steady loop step 2: o*fd multiplies moved into the slot that waited for the QK MFMA results
# baseline (speedup 1.0000x reference)
.LBB0_362:
	s_add_i32 s46, s1, 0x2000
	s_cmpk_lg_i32 s1, 0x4000
	s_cselect_b32 s46, s46, 0
	v_add_u32_e32 v187, s50, v249
	ds_read_b64_tr_b16 v[56:57], v187 offset:24576
	ds_read_b64_tr_b16 v[58:59], v187 offset:25088
	s_waitcnt lgkmcnt(9)
	v_mfma_f32_32x32x16_bf16 v[82:97], v[114:117], v[150:153], v[66:81]
	v_add_f32_e32 v34, v36, v37
	v_add_f32_e32 v34, v38, v34
	v_add_f32_e32 v34, v39, v34
	v_add_f32_e32 v34, v40, v34
	v_add_f32_e32 v34, v41, v34
	v_cvt_pk_bf16_f32 v158, v36, v37
	v_cvt_pk_bf16_f32 v159, v38, v39
	ds_read_b64_tr_b16 v[52:53], v187 offset:28672
	ds_read_b64_tr_b16 v[54:55], v187 offset:29184
	v_add_f32_e32 v34, v42, v34
	v_add_f32_e32 v34, v43, v34
	v_add_f32_e32 v34, v44, v34
	v_add_f32_e32 v38, v45, v34
	v_cvt_pk_bf16_f32 v160, v40, v41
	v_cvt_pk_bf16_f32 v161, v42, v43
	s_waitcnt lgkmcnt(10)
	v_mfma_f32_32x32x16_bf16 v[114:129], v[178:181], v[150:153], v[66:81]
	ds_read_b64_tr_b16 v[34:35], v187 offset:25600
	ds_read_b64_tr_b16 v[36:37], v187 offset:26112
	s_waitcnt lgkmcnt(11)
	v_mfma_f32_32x32x16_bf16 v[82:97], v[182:185], v[142:145], v[82:97]
	v_add_f32_e32 v38, v46, v38
	v_add_f32_e32 v38, v47, v38
	v_add_f32_e32 v38, v48, v38
	v_add_f32_e32 v42, v49, v38
	v_cvt_pk_bf16_f32 v154, v44, v45
	v_cvt_pk_bf16_f32 v155, v46, v47
	ds_read_b64_tr_b16 v[38:39], v187 offset:29696
	ds_read_b64_tr_b16 v[40:41], v187 offset:30208
	v_add_f32_e32 v42, v50, v42
	v_add_f32_e32 v42, v51, v42
	v_add_f32_e32 v42, v98, v42
	v_add_f32_e32 v46, v99, v42
	v_cvt_pk_bf16_f32 v156, v48, v49
	v_cvt_pk_bf16_f32 v157, v50, v51
	s_waitcnt lgkmcnt(12)
	v_mfma_f32_32x32x16_bf16 v[114:129], v[174:177], v[142:145], v[114:129]
	ds_read_b64_tr_b16 v[42:43], v187 offset:26624
	ds_read_b64_tr_b16 v[44:45], v187 offset:27136
	s_waitcnt lgkmcnt(13)
	v_mfma_f32_32x32x16_bf16 v[82:97], v[170:173], v[134:137], v[82:97]
	v_add_f32_e32 v46, v100, v46
	v_add_f32_e32 v46, v101, v46
	v_add_f32_e32 v46, v102, v46
	v_add_f32_e32 v50, v103, v46
	v_cvt_pk_bf16_f32 v146, v98, v99
	v_cvt_pk_bf16_f32 v147, v100, v101
	ds_read_b64_tr_b16 v[46:47], v187 offset:30720
	ds_read_b64_tr_b16 v[48:49], v187 offset:31232
	v_add_f32_e32 v50, v104, v50
	v_add_f32_e32 v50, v105, v50
	v_add_f32_e32 v50, v106, v50
	v_add_f32_e32 v50, v107, v50
	v_cvt_pk_bf16_f32 v148, v102, v103
	v_cvt_pk_bf16_f32 v149, v104, v105
	s_waitcnt lgkmcnt(14)
	v_mfma_f32_32x32x16_bf16 v[114:129], v[60:63], v[134:137], v[114:129]
	ds_read_b64_tr_b16 v[60:61], v187 offset:27648
	ds_read_b64_tr_b16 v[62:63], v187 offset:28160
	s_waitcnt lgkmcnt(14)
	v_mfma_f32_32x32x16_bf16 v[82:97], v[166:169], v[130:133], v[82:97]
	v_add_f32_e32 v50, v108, v50
	v_add_f32_e32 v50, v109, v50
	v_add_f32_e32 v50, v110, v50
	v_add_f32_e32 v50, v111, v50
	v_cvt_pk_bf16_f32 v138, v106, v107
	v_cvt_pk_bf16_f32 v139, v108, v109
	ds_read_b64_tr_b16 v[194:195], v187 offset:31744
	ds_read_b64_tr_b16 v[196:197], v187 offset:32256
	v_add_f32_e32 v50, v112, v50
	v_add_f32_e32 v50, v113, v50
	v_cvt_pk_bf16_f32 v140, v110, v111
	v_cvt_pk_bf16_f32 v141, v112, v113
	v_mfma_f32_32x32x16_bf16 v[114:129], v[162:165], v[130:133], v[114:129]
	v_pk_mul_f32 v[32:33], v[210:211], v[32:33]
	v_pk_mul_f32 v[30:31], v[210:211], v[30:31]
	v_pk_mul_f32 v[28:29], v[210:211], v[28:29]
	v_pk_mul_f32 v[26:27], v[210:211], v[26:27]
	v_pk_mul_f32 v[24:25], v[210:211], v[24:25]
	v_pk_mul_f32 v[22:23], v[210:211], v[22:23]
	v_pk_mul_f32 v[20:21], v[210:211], v[20:21]
	v_pk_mul_f32 v[18:19], v[64:65], v[18:19]
	v_pk_mul_f32 v[16:17], v[210:211], v[16:17]
	v_pk_mul_f32 v[14:15], v[210:211], v[14:15]
	v_pk_mul_f32 v[12:13], v[210:211], v[12:13]
	v_pk_mul_f32 v[10:11], v[210:211], v[10:11]
	v_pk_mul_f32 v[8:9], v[210:211], v[8:9]
	v_pk_mul_f32 v[6:7], v[210:211], v[6:7]
	v_pk_mul_f32 v[4:5], v[210:211], v[4:5]
	v_pk_mul_f32 v[2:3], v[64:65], v[2:3]
	v_pk_add_f32 v[98:99], v[220:221], v[114:115]
	v_pk_add_f32 v[100:101], v[214:215], v[116:117]
	v_max_f32_e32 v51, v82, v83
	v_max3_f32 v114, v84, v85, v99
	v_max3_f32 v51, v51, v98, v100
	v_pk_add_f32 v[104:105], v[214:215], v[120:121]
	v_pk_add_f32 v[102:103], v[214:215], v[118:119]
	v_max3_f32 v51, v51, v101, v86
	v_max3_f32 v114, v114, v88, v89
	v_max3_f32 v51, v51, v87, v102
	v_max3_f32 v114, v114, v104, v105
	v_pk_add_f32 v[108:109], v[214:215], v[124:125]
	v_pk_add_f32 v[106:107], v[214:215], v[122:123]
	v_max3_f32 v51, v51, v103, v90
	v_max3_f32 v114, v114, v92, v93
	v_max3_f32 v51, v51, v91, v106
	v_max3_f32 v114, v114, v108, v109
	v_pk_add_f32 v[112:113], v[214:215], v[128:129]
	v_pk_add_f32 v[110:111], v[214:215], v[126:127]
	v_max3_f32 v51, v51, v107, v94
	v_max3_f32 v114, v114, v96, v97
	v_max3_f32 v51, v51, v95, v110
	v_max3_f32 v114, v114, v112, v113
	v_max3_f32 v51, v51, v111, v114
	v_mov_b32_e32 v114, v51
	s_nop 1
	v_permlane32_swap_b32_e32 v51, v114
	s_add_i32 s48, s1, s29
	s_mov_b32 s50, m0
	s_mov_b32 m0, s48
	s_nop 0
	global_load_lds_dwordx4 v[224:225], off
	s_mov_b32 m0, s50
	v_max_f32_e32 v51, v51, v114
	s_add_i32 s48, s46, s44
	s_mov_b32 s50, m0
	s_mov_b32 m0, s48
	s_nop 0
	global_load_lds_dwordx4 v[222:223], off
	s_mov_b32 m0, s50
	v_cmp_lt_f32_e32 vcc, s88, v51
	s_cmp_lg_u64 vcc, 0
	v_fmac_f32_e32 v50, v210, v186
	s_cselect_b64 s[52:53], -1, 0
	s_cbranch_vccnz .LBB0_370
.LBB0_363:
	s_waitcnt lgkmcnt(14)
	s_nop 0
	v_mfma_f32_32x32x16_bf16 v[2:17], v[158:161], v[56:59], v[2:17]
	v_exp_f32_e32 v82, v82
	v_exp_f32_e32 v83, v83
	v_exp_f32_e32 v84, v84
	v_exp_f32_e32 v85, v85
	s_waitcnt lgkmcnt(12)
	v_mfma_f32_32x32x16_bf16 v[18:33], v[158:161], v[52:55], v[18:33]
	v_exp_f32_e32 v86, v86
	v_exp_f32_e32 v87, v87
	v_exp_f32_e32 v88, v88
	v_exp_f32_e32 v89, v89
	v_add_u32_e32 v51, s46, v248
	ds_read_b128 v[190:193], v51
	ds_read_b128 v[186:189], v51 offset:512
	s_waitcnt lgkmcnt(12)
	v_mfma_f32_32x32x16_bf16 v[2:17], v[154:157], v[34:37], v[2:17]
	v_exp_f32_e32 v90, v90
	v_exp_f32_e32 v91, v91
	v_exp_f32_e32 v92, v92
	v_exp_f32_e32 v93, v93
	ds_read_b128 v[182:185], v51 offset:2048
	ds_read_b128 v[178:181], v51 offset:2560
	s_waitcnt lgkmcnt(12)
	v_mfma_f32_32x32x16_bf16 v[18:33], v[154:157], v[38:41], v[18:33]
	v_exp_f32_e32 v94, v94
	v_exp_f32_e32 v95, v95
	v_exp_f32_e32 v96, v96
	v_exp_f32_e32 v97, v97
	ds_read_b128 v[174:177], v51 offset:4096
	ds_read_b128 v[170:173], v51 offset:4608
	s_waitcnt lgkmcnt(12)
	v_mfma_f32_32x32x16_bf16 v[2:17], v[146:149], v[42:45], v[2:17]
	v_exp_f32_e32 v98, v98
	v_exp_f32_e32 v99, v99
	v_exp_f32_e32 v100, v100
	v_exp_f32_e32 v101, v101
	ds_read_b128 v[166:169], v51 offset:6144
	ds_read_b128 v[162:165], v51 offset:6656
	s_waitcnt lgkmcnt(12)
	v_mfma_f32_32x32x16_bf16 v[18:33], v[146:149], v[46:49], v[18:33]
	v_exp_f32_e32 v102, v102
	v_exp_f32_e32 v103, v103
	v_exp_f32_e32 v104, v104
	v_exp_f32_e32 v105, v105
	s_waitcnt lgkmcnt(10)
	v_mfma_f32_32x32x16_bf16 v[2:17], v[138:141], v[60:63], v[2:17]
	v_exp_f32_e32 v106, v106
	v_exp_f32_e32 v107, v107
	v_exp_f32_e32 v108, v108
	v_exp_f32_e32 v109, v109
	s_waitcnt lgkmcnt(8)
	v_mfma_f32_32x32x16_bf16 v[18:33], v[138:141], v[194:197], v[18:33]
	v_exp_f32_e32 v110, v110
	v_exp_f32_e32 v111, v111
	v_exp_f32_e32 v112, v112
	v_exp_f32_e32 v113, v113
	s_waitcnt vmcnt(2) lgkmcnt(0)
	s_barrier
	s_andn2_b64 vcc, exec, s[52:53]
	s_cbranch_vccnz .LBB0_365
	s_waitcnt lgkmcnt(0)
	ds_read_b128 v[34:37], v242 offset:49248
	ds_read_b128 v[38:41], v242 offset:49216
	ds_read_b128 v[42:45], v242 offset:49184
	ds_read_b128 v[46:49], v242 offset:49152
	s_waitcnt lgkmcnt(3)
	v_pk_mul_f32 v[16:17], v[16:17], v[36:37]
	s_waitcnt lgkmcnt(2)
	v_pk_mul_f32 v[12:13], v[12:13], v[40:41]
	s_waitcnt lgkmcnt(1)
	v_pk_mul_f32 v[8:9], v[8:9], v[44:45]
	s_waitcnt lgkmcnt(0)
	v_pk_mul_f32 v[4:5], v[4:5], v[48:49]
	v_pk_mul_f32 v[14:15], v[14:15], v[34:35]
	v_pk_mul_f32 v[10:11], v[10:11], v[38:39]
	v_pk_mul_f32 v[6:7], v[6:7], v[42:43]
	v_pk_mul_f32 v[2:3], v[2:3], v[46:47]
	v_pk_mul_f32 v[32:33], v[32:33], v[36:37]
	v_pk_mul_f32 v[28:29], v[28:29], v[40:41]
	v_pk_mul_f32 v[24:25], v[24:25], v[44:45]
	v_pk_mul_f32 v[20:21], v[20:21], v[48:49]
	v_pk_mul_f32 v[30:31], v[30:31], v[34:35]
	v_pk_mul_f32 v[26:27], v[26:27], v[38:39]
	v_pk_mul_f32 v[22:23], v[22:23], v[42:43]
	v_pk_mul_f32 v[18:19], v[18:19], v[46:47]
